# HM filler stores write-through (sc1): ack absorbed in the barrier idle time, less dirty L2 for the next barrier
# speedup vs baseline: 1.0058x; 1.0034x over previous
; __device__ __forceinline__ void st_wt16(void* p, u32x4 v) { asm volatile("global_store_dwordx4 %0, %1, off sc1\n\ts_nop 1" : : "v"(p), "v"(v) : "memory"); }
; __device__ __forceinline__ void p5_fixup(const Params& p) {
;     ...
;     for (int v0 = gtid; v0 < T_TOK * 128; v0 += 4 * gsz) {
;         u32x4 hv[4]; float4 s0[4], s1[4];
; #pragma unroll
;         for (int u = 0; u < 4; ++u) { const int v = v0 + u * gsz; if (v < T_TOK * 128) { const int row = v >> 7, head = (v >> 5) & 3;
;             hv[u] = __builtin_nontemporal_load((const u32x4*)(HM + (size_t)v * 8)); s0[u] = *(const float4*)(SSQ + ((size_t)row * 4 + head) * 8); s1[u] = *(const float4*)(SSQ + ((size_t)row * 4 + head) * 8 + 4); } }
; #pragma unroll
;         for (int u = 0; u < 4; ++u) { const int v = v0 + u * gsz; if (v < T_TOK * 128) {
;             const float ss = (s0[u].x + s0[u].y) + (s0[u].z + s0[u].w) + (s1[u].x + s1[u].y) + (s1[u].z + s1[u].w);
;             const float rstd = rsqrtf(ss * (1.0f / 256.0f) + EPS);
;             float f[8]; unpack8(hv[u], f);
; #pragma unroll
;             for (int e = 0; e < 8; ++e) f[e] *= rstd;
;             st_wt16(HM + (size_t)v * 8, pack8(f)); } }
.Lattn_perm_done:
	s_mov_b32 s99, 0
	s_cmp_lt_i32 s90, 6
	s_cselect_b64 s[0:1], -1, 0
	s_and_b64 s[96:97], s[0:1], s[2:3]
	s_andn2_b64 vcc, exec, s[96:97]
	s_cbranch_vccnz .LBB0_629
	s_cmp_eq_u32 s82, 0x100
	s_cbranch_scc0 .Lf4_done
	v_readlane_b32 s96, v254, 23
	v_readlane_b32 s97, v254, 24
	v_lshlrev_b32_e32 v64, 4, v212
	v_mov_b32_e32 v65, s84
	v_lshl_add_u32 v64, v65, 15, v64
	v_lshlrev_b32_e32 v65, 11, v65
	v_and_b32_e32 v60, 0x1e0, v212
	v_add_u32_e32 v65, v65, v60
	v_and_b32_e32 v60, 7, v212
	v_lshl_add_u32 v65, v60, 2, v65
	v_add_u32_e32 v65, 0xfd80000, v65
	s_nop 4
	v_mov_b32_e32 v62, v64
	global_load_dwordx4 v[20:23], v62, s[96:97] nt
	v_add_u32_e32 v62, 0x2000, v64
	global_load_dwordx4 v[24:27], v62, s[96:97] nt
	v_add_u32_e32 v62, 0x4000, v64
	global_load_dwordx4 v[28:31], v62, s[96:97] nt
	v_add_u32_e32 v62, 0x6000, v64
	global_load_dwordx4 v[32:35], v62, s[96:97] nt
	v_add_u32_e32 v62, 0x800000, v64
	global_load_dwordx4 v[36:39], v62, s[96:97] nt
	v_add_u32_e32 v62, 0x802000, v64
	global_load_dwordx4 v[40:43], v62, s[96:97] nt
	v_add_u32_e32 v62, 0x804000, v64
	global_load_dwordx4 v[44:47], v62, s[96:97] nt
	v_add_u32_e32 v62, 0x806000, v64
	global_load_dwordx4 v[48:51], v62, s[96:97] nt
	v_mov_b32_e32 v62, v65
	global_load_dword v52, v62, s[88:89]
	v_add_u32_e32 v62, 0x200, v65
	global_load_dword v53, v62, s[88:89]
	v_add_u32_e32 v62, 0x400, v65
	global_load_dword v54, v62, s[88:89]
	v_add_u32_e32 v62, 0x600, v65
	global_load_dword v55, v62, s[88:89]
	v_add_u32_e32 v62, 0x80000, v65
	global_load_dword v56, v62, s[88:89]
	v_add_u32_e32 v62, 0x80200, v65
	global_load_dword v57, v62, s[88:89]
	v_add_u32_e32 v62, 0x80400, v65
	global_load_dword v58, v62, s[88:89]
	v_add_u32_e32 v62, 0x80600, v65
	global_load_dword v59, v62, s[88:89]
	s_waitcnt vmcnt(0)
	v_add_f32_dpp v52, v52, v52 quad_perm:[1,0,3,2] row_mask:0xf bank_mask:0xf
	v_add_f32_dpp v53, v53, v53 quad_perm:[1,0,3,2] row_mask:0xf bank_mask:0xf
	v_add_f32_dpp v54, v54, v54 quad_perm:[1,0,3,2] row_mask:0xf bank_mask:0xf
	v_add_f32_dpp v55, v55, v55 quad_perm:[1,0,3,2] row_mask:0xf bank_mask:0xf
	v_add_f32_dpp v56, v56, v56 quad_perm:[1,0,3,2] row_mask:0xf bank_mask:0xf
	v_add_f32_dpp v57, v57, v57 quad_perm:[1,0,3,2] row_mask:0xf bank_mask:0xf
	v_add_f32_dpp v58, v58, v58 quad_perm:[1,0,3,2] row_mask:0xf bank_mask:0xf
	v_add_f32_dpp v59, v59, v59 quad_perm:[1,0,3,2] row_mask:0xf bank_mask:0xf
	v_add_f32_dpp v52, v52, v52 quad_perm:[2,3,0,1] row_mask:0xf bank_mask:0xf
	v_add_f32_dpp v53, v53, v53 quad_perm:[2,3,0,1] row_mask:0xf bank_mask:0xf
	v_add_f32_dpp v54, v54, v54 quad_perm:[2,3,0,1] row_mask:0xf bank_mask:0xf
	v_add_f32_dpp v55, v55, v55 quad_perm:[2,3,0,1] row_mask:0xf bank_mask:0xf
	v_add_f32_dpp v56, v56, v56 quad_perm:[2,3,0,1] row_mask:0xf bank_mask:0xf
	v_add_f32_dpp v57, v57, v57 quad_perm:[2,3,0,1] row_mask:0xf bank_mask:0xf
	v_add_f32_dpp v58, v58, v58 quad_perm:[2,3,0,1] row_mask:0xf bank_mask:0xf
	v_add_f32_dpp v59, v59, v59 quad_perm:[2,3,0,1] row_mask:0xf bank_mask:0xf
	v_add_f32_dpp v52, v52, v52 row_half_mirror row_mask:0xf bank_mask:0xf
	v_add_f32_dpp v53, v53, v53 row_half_mirror row_mask:0xf bank_mask:0xf
	v_add_f32_dpp v54, v54, v54 row_half_mirror row_mask:0xf bank_mask:0xf
	v_add_f32_dpp v55, v55, v55 row_half_mirror row_mask:0xf bank_mask:0xf
	v_add_f32_dpp v56, v56, v56 row_half_mirror row_mask:0xf bank_mask:0xf
	v_add_f32_dpp v57, v57, v57 row_half_mirror row_mask:0xf bank_mask:0xf
	v_add_f32_dpp v58, v58, v58 row_half_mirror row_mask:0xf bank_mask:0xf
	v_add_f32_dpp v59, v59, v59 row_half_mirror row_mask:0xf bank_mask:0xf
	v_mov_b32_e32 v60, 0x358637bd
	v_fmamk_f32 v52, v52, 0x3b800000, v60
	v_fmamk_f32 v53, v53, 0x3b800000, v60
	v_fmamk_f32 v54, v54, 0x3b800000, v60
	v_fmamk_f32 v55, v55, 0x3b800000, v60
	v_fmamk_f32 v56, v56, 0x3b800000, v60
	v_fmamk_f32 v57, v57, 0x3b800000, v60
	v_fmamk_f32 v58, v58, 0x3b800000, v60
	v_fmamk_f32 v59, v59, 0x3b800000, v60
	v_rsq_f32_e32 v52, v52
	v_rsq_f32_e32 v53, v53
	v_rsq_f32_e32 v54, v54
	v_rsq_f32_e32 v55, v55
	v_rsq_f32_e32 v56, v56
	v_rsq_f32_e32 v57, v57
	v_rsq_f32_e32 v58, v58
	v_rsq_f32_e32 v59, v59
	s_nop 0
	v_lshlrev_b32_e32 v62, 16, v20
	v_and_b32_e32 v63, 0xffff0000, v20
	v_mul_f32_e32 v62, v52, v62
	v_mul_f32_e32 v63, v52, v63
	v_cvt_pk_bf16_f32 v20, v62, v63
	v_lshlrev_b32_e32 v62, 16, v21
	v_and_b32_e32 v63, 0xffff0000, v21
	v_mul_f32_e32 v62, v52, v62
	v_mul_f32_e32 v63, v52, v63
	v_cvt_pk_bf16_f32 v21, v62, v63
	v_lshlrev_b32_e32 v62, 16, v22
	v_and_b32_e32 v63, 0xffff0000, v22
	v_mul_f32_e32 v62, v52, v62
	v_mul_f32_e32 v63, v52, v63
	v_cvt_pk_bf16_f32 v22, v62, v63
	v_lshlrev_b32_e32 v62, 16, v23
	v_and_b32_e32 v63, 0xffff0000, v23
	v_mul_f32_e32 v62, v52, v62
	v_mul_f32_e32 v63, v52, v63
	v_cvt_pk_bf16_f32 v23, v62, v63
	v_mov_b32_e32 v62, v64
	global_store_dwordx4 v62, v[20:23], s[96:97] sc1
	v_lshlrev_b32_e32 v62, 16, v24
	v_and_b32_e32 v63, 0xffff0000, v24
	v_mul_f32_e32 v62, v53, v62
; __device__ __forceinline__ void st_wt16(void* p, u32x4 v) { asm volatile("global_store_dwordx4 %0, %1, off sc1\n\ts_nop 1" : : "v"(p), "v"(v) : "memory"); }
; __device__ __forceinline__ void p5_fixup(const Params& p) {
;     ...
;         for (int u = 0; u < 4; ++u) { const int v = v0 + u * gsz; if (v < T_TOK * 128) {
;             const float ss = (s0[u].x + s0[u].y) + (s0[u].z + s0[u].w) + (s1[u].x + s1[u].y) + (s1[u].z + s1[u].w);
;             const float rstd = rsqrtf(ss * (1.0f / 256.0f) + EPS);
;             float f[8]; unpack8(hv[u], f);
; #pragma unroll
;             for (int e = 0; e < 8; ++e) f[e] *= rstd;
;             st_wt16(HM + (size_t)v * 8, pack8(f)); } }
	v_mul_f32_e32 v63, v53, v63
	v_cvt_pk_bf16_f32 v24, v62, v63
	v_lshlrev_b32_e32 v62, 16, v25
	v_and_b32_e32 v63, 0xffff0000, v25
	v_mul_f32_e32 v62, v53, v62
	v_mul_f32_e32 v63, v53, v63
	v_cvt_pk_bf16_f32 v25, v62, v63
	v_lshlrev_b32_e32 v62, 16, v26
	v_and_b32_e32 v63, 0xffff0000, v26
	v_mul_f32_e32 v62, v53, v62
	v_mul_f32_e32 v63, v53, v63
	v_cvt_pk_bf16_f32 v26, v62, v63
	v_lshlrev_b32_e32 v62, 16, v27
	v_and_b32_e32 v63, 0xffff0000, v27
	v_mul_f32_e32 v62, v53, v62
	v_mul_f32_e32 v63, v53, v63
	v_cvt_pk_bf16_f32 v27, v62, v63
	v_add_u32_e32 v62, 0x2000, v64
	global_store_dwordx4 v62, v[24:27], s[96:97] sc1
	v_lshlrev_b32_e32 v62, 16, v28
	v_and_b32_e32 v63, 0xffff0000, v28
	v_mul_f32_e32 v62, v54, v62
	v_mul_f32_e32 v63, v54, v63
	v_cvt_pk_bf16_f32 v28, v62, v63
	v_lshlrev_b32_e32 v62, 16, v29
	v_and_b32_e32 v63, 0xffff0000, v29
	v_mul_f32_e32 v62, v54, v62
	v_mul_f32_e32 v63, v54, v63
	v_cvt_pk_bf16_f32 v29, v62, v63
	v_lshlrev_b32_e32 v62, 16, v30
	v_and_b32_e32 v63, 0xffff0000, v30
	v_mul_f32_e32 v62, v54, v62
	v_mul_f32_e32 v63, v54, v63
	v_cvt_pk_bf16_f32 v30, v62, v63
	v_lshlrev_b32_e32 v62, 16, v31
	v_and_b32_e32 v63, 0xffff0000, v31
	v_mul_f32_e32 v62, v54, v62
	v_mul_f32_e32 v63, v54, v63
	v_cvt_pk_bf16_f32 v31, v62, v63
	v_add_u32_e32 v62, 0x4000, v64
	global_store_dwordx4 v62, v[28:31], s[96:97] sc1
	v_lshlrev_b32_e32 v62, 16, v32
	v_and_b32_e32 v63, 0xffff0000, v32
	v_mul_f32_e32 v62, v55, v62
	v_mul_f32_e32 v63, v55, v63
	v_cvt_pk_bf16_f32 v32, v62, v63
	v_lshlrev_b32_e32 v62, 16, v33
	v_and_b32_e32 v63, 0xffff0000, v33
	v_mul_f32_e32 v62, v55, v62
	v_mul_f32_e32 v63, v55, v63
	v_cvt_pk_bf16_f32 v33, v62, v63
	v_lshlrev_b32_e32 v62, 16, v34
	v_and_b32_e32 v63, 0xffff0000, v34
	v_mul_f32_e32 v62, v55, v62
	v_mul_f32_e32 v63, v55, v63
	v_cvt_pk_bf16_f32 v34, v62, v63
	v_lshlrev_b32_e32 v62, 16, v35
	v_and_b32_e32 v63, 0xffff0000, v35
	v_mul_f32_e32 v62, v55, v62
	v_mul_f32_e32 v63, v55, v63
	v_cvt_pk_bf16_f32 v35, v62, v63
	v_add_u32_e32 v62, 0x6000, v64
	global_store_dwordx4 v62, v[32:35], s[96:97] sc1
	v_lshlrev_b32_e32 v62, 16, v36
	v_and_b32_e32 v63, 0xffff0000, v36
	v_mul_f32_e32 v62, v56, v62
	v_mul_f32_e32 v63, v56, v63
	v_cvt_pk_bf16_f32 v36, v62, v63
	v_lshlrev_b32_e32 v62, 16, v37
	v_and_b32_e32 v63, 0xffff0000, v37
	v_mul_f32_e32 v62, v56, v62
	v_mul_f32_e32 v63, v56, v63
	v_cvt_pk_bf16_f32 v37, v62, v63
	v_lshlrev_b32_e32 v62, 16, v38
	v_and_b32_e32 v63, 0xffff0000, v38
	v_mul_f32_e32 v62, v56, v62
	v_mul_f32_e32 v63, v56, v63
	v_cvt_pk_bf16_f32 v38, v62, v63
	v_lshlrev_b32_e32 v62, 16, v39
	v_and_b32_e32 v63, 0xffff0000, v39
	v_mul_f32_e32 v62, v56, v62
	v_mul_f32_e32 v63, v56, v63
	v_cvt_pk_bf16_f32 v39, v62, v63
	v_add_u32_e32 v62, 0x800000, v64
	global_store_dwordx4 v62, v[36:39], s[96:97] sc1
	v_lshlrev_b32_e32 v62, 16, v40
	v_and_b32_e32 v63, 0xffff0000, v40
	v_mul_f32_e32 v62, v57, v62
	v_mul_f32_e32 v63, v57, v63
	v_cvt_pk_bf16_f32 v40, v62, v63
	v_lshlrev_b32_e32 v62, 16, v41
	v_and_b32_e32 v63, 0xffff0000, v41
	v_mul_f32_e32 v62, v57, v62
	v_mul_f32_e32 v63, v57, v63
	v_cvt_pk_bf16_f32 v41, v62, v63
	v_lshlrev_b32_e32 v62, 16, v42
	v_and_b32_e32 v63, 0xffff0000, v42
	v_mul_f32_e32 v62, v57, v62
	v_mul_f32_e32 v63, v57, v63
	v_cvt_pk_bf16_f32 v42, v62, v63
	v_lshlrev_b32_e32 v62, 16, v43
	v_and_b32_e32 v63, 0xffff0000, v43
	v_mul_f32_e32 v62, v57, v62
	v_mul_f32_e32 v63, v57, v63
	v_cvt_pk_bf16_f32 v43, v62, v63
	v_add_u32_e32 v62, 0x802000, v64
	global_store_dwordx4 v62, v[40:43], s[96:97] sc1
	v_lshlrev_b32_e32 v62, 16, v44
	v_and_b32_e32 v63, 0xffff0000, v44
	v_mul_f32_e32 v62, v58, v62
	v_mul_f32_e32 v63, v58, v63
	v_cvt_pk_bf16_f32 v44, v62, v63
	v_lshlrev_b32_e32 v62, 16, v45
	v_and_b32_e32 v63, 0xffff0000, v45
	v_mul_f32_e32 v62, v58, v62
	v_mul_f32_e32 v63, v58, v63
	v_cvt_pk_bf16_f32 v45, v62, v63
	v_lshlrev_b32_e32 v62, 16, v46
	v_and_b32_e32 v63, 0xffff0000, v46
	v_mul_f32_e32 v62, v58, v62
	v_mul_f32_e32 v63, v58, v63
	v_cvt_pk_bf16_f32 v46, v62, v63
	v_lshlrev_b32_e32 v62, 16, v47
	v_and_b32_e32 v63, 0xffff0000, v47
	v_mul_f32_e32 v62, v58, v62
	v_mul_f32_e32 v63, v58, v63
	v_cvt_pk_bf16_f32 v47, v62, v63
	v_add_u32_e32 v62, 0x804000, v64
	global_store_dwordx4 v62, v[44:47], s[96:97] sc1
	v_lshlrev_b32_e32 v62, 16, v48
	v_and_b32_e32 v63, 0xffff0000, v48
	v_mul_f32_e32 v62, v59, v62
	v_mul_f32_e32 v63, v59, v63
	v_cvt_pk_bf16_f32 v48, v62, v63
	v_lshlrev_b32_e32 v62, 16, v49
	v_and_b32_e32 v63, 0xffff0000, v49
	v_mul_f32_e32 v62, v59, v62
	v_mul_f32_e32 v63, v59, v63
	v_cvt_pk_bf16_f32 v49, v62, v63
	v_lshlrev_b32_e32 v62, 16, v50
	v_and_b32_e32 v63, 0xffff0000, v50
	v_mul_f32_e32 v62, v59, v62
	v_mul_f32_e32 v63, v59, v63
	v_cvt_pk_bf16_f32 v50, v62, v63
	v_lshlrev_b32_e32 v62, 16, v51
	v_and_b32_e32 v63, 0xffff0000, v51
	v_mul_f32_e32 v62, v59, v62
	v_mul_f32_e32 v63, v59, v63
	v_cvt_pk_bf16_f32 v51, v62, v63
	v_add_u32_e32 v62, 0x806000, v64
	global_store_dwordx4 v62, v[48:51], s[96:97] sc1
	s_nop 1
